# attention: V fragments read straight into MFMA operand quads (no v_mov shuffles), row-max tree 11->4 VALU; hazards re-padded
# speedup vs baseline: 1.0774x; 1.0356x over previous
.LBB0_701:
	v_sub_f32_e32 v52, v52, v56
	v_exp_f32_e32 v59, v52
	v_sub_f32_e32 v52, v53, v56
	v_sub_f32_e32 v48, v48, v56
	v_exp_f32_e32 v53, v52
	v_sub_f32_e32 v52, v54, v56
	v_exp_f32_e32 v63, v48
	v_sub_f32_e32 v48, v49, v56
	v_sub_f32_e32 v44, v44, v57
	v_exp_f32_e32 v61, v52
	v_sub_f32_e32 v52, v55, v56
	v_exp_f32_e32 v49, v48
	v_sub_f32_e32 v48, v50, v56
	v_exp_f32_e32 v58, v44
	v_sub_f32_e32 v44, v45, v57
	v_sub_f32_e32 v40, v40, v57
	v_exp_f32_e32 v55, v52
	v_exp_f32_e32 v65, v48
	v_sub_f32_e32 v48, v51, v56
	v_exp_f32_e32 v52, v44
	v_sub_f32_e32 v44, v46, v57
	v_exp_f32_e32 v62, v40
	v_sub_f32_e32 v40, v41, v57
	v_exp_f32_e32 v51, v48
	v_exp_f32_e32 v60, v44
	v_sub_f32_e32 v44, v47, v57
	v_exp_f32_e32 v48, v40
	v_sub_f32_e32 v40, v42, v57
	v_exp_f32_e32 v54, v44
	v_exp_f32_e32 v64, v40
	v_sub_f32_e32 v40, v43, v57
	v_exp_f32_e32 v50, v40
	v_pk_add_f32 v[40:41], v[58:59], 0 op_sel_hi:[1,0]
	v_cvt_pk_bf16_f32 v214, v59, v53
	v_pk_add_f32 v[40:41], v[52:53], v[40:41]
	v_cvt_pk_bf16_f32 v215, v61, v55
	v_pk_add_f32 v[40:41], v[60:61], v[40:41]
	v_cvt_pk_bf16_f32 v216, v63, v49
	v_pk_add_f32 v[40:41], v[54:55], v[40:41]
	v_cvt_pk_bf16_f32 v217, v65, v51
	v_pk_add_f32 v[40:41], v[62:63], v[40:41]
	v_cvt_pk_bf16_f32 v218, v58, v52
	v_pk_add_f32 v[40:41], v[48:49], v[40:41]
	v_cvt_pk_bf16_f32 v219, v60, v54
	v_pk_add_f32 v[40:41], v[64:65], v[40:41]
	v_cvt_pk_bf16_f32 v220, v62, v48
	v_pk_add_f32 v[40:41], v[50:51], v[40:41]
	v_cvt_pk_bf16_f32 v221, v64, v50
	v_pk_add_f32 v[174:175], v[176:177], v[40:41]
	s_setprio 1
	s_waitcnt lgkmcnt(0)
	s_nop 1
	v_mfma_f32_16x16x32_bf16 v[56:59], v[32:35], v[214:217], v[124:127]
	v_mfma_f32_16x16x32_bf16 v[60:63], v[32:35], v[218:221], v[120:123]
	v_mfma_f32_16x16x32_bf16 v[64:67], v[36:39], v[214:217], v[132:135]
	v_mfma_f32_16x16x32_bf16 v[68:71], v[36:39], v[218:221], v[128:131]
	v_mfma_f32_16x16x32_bf16 v[40:43], v[24:27], v[214:217], v[108:111]
	v_mfma_f32_16x16x32_bf16 v[44:47], v[24:27], v[218:221], v[104:107]
	v_mfma_f32_16x16x32_bf16 v[48:51], v[28:31], v[214:217], v[116:119]
	v_mfma_f32_16x16x32_bf16 v[52:55], v[28:31], v[218:221], v[112:115]
	v_mfma_f32_16x16x32_bf16 v[32:35], v[20:23], v[214:217], v[100:103]
	v_mfma_f32_16x16x32_bf16 v[36:39], v[20:23], v[218:221], v[96:99]
	v_mfma_f32_16x16x32_bf16 v[24:27], v[16:19], v[214:217], v[92:95]
	v_mfma_f32_16x16x32_bf16 v[28:31], v[16:19], v[218:221], v[88:91]
	v_mfma_f32_16x16x32_bf16 v[16:19], v[140:143], v[214:217], v[84:87]
	v_mfma_f32_16x16x32_bf16 v[20:23], v[140:143], v[218:221], v[80:83]
	v_mfma_f32_16x16x32_bf16 v[72:75], v[136:139], v[214:217], v[72:75]
	v_mfma_f32_16x16x32_bf16 v[76:79], v[136:139], v[218:221], v[76:79]
	s_setprio 0
	s_add_i32 s14, s14, 0x10000
	s_waitcnt vmcnt(0)
	s_add_u32 s10, s10, 0x40000
	s_addc_u32 s11, s11, 0
	s_add_i32 s13, s13, 1
	v_lshl_add_u64 v[154:155], v[154:155], 0, s[6:7]
	v_lshl_add_u64 v[156:157], v[156:157], 0, s[6:7]
	v_lshl_add_u64 v[158:159], v[158:159], 0, s[6:7]
	s_cmp_eq_u32 s2, s10
	v_lshl_add_u64 v[160:161], v[160:161], 0, s[6:7]
	s_barrier
	s_cbranch_scc1 .LBB0_685

.LBB0_704:
	s_and_b32 s0, s14, 0x10000
	s_add_i32 s17, s0, 0
	v_add_u32_e32 v88, s17, v192
	v_add_u32_e32 v149, v88, v195
	v_add_u32_e32 v151, v88, v196
	v_add_u32_e32 v214, v88, v197
	v_add_u32_e32 v215, v88, v198
	v_add_u32_e32 v88, s17, v193
	v_add_u32_e32 v89, s17, v199
	ds_read_b128 v[80:83], v149
	ds_read_b128 v[84:87], v149 offset:4096
	ds_read_b128 v[120:123], v151
	ds_read_b128 v[128:131], v151 offset:4096
	ds_read_b128 v[132:135], v214
	ds_read_b128 v[136:139], v214 offset:4096
	ds_read_b128 v[140:143], v215
	ds_read_b128 v[216:219], v215 offset:4096
	s_waitcnt vmcnt(0)
	ds_read_b64 v[116:117], v88 offset:32768
	ds_read_b64 v[118:119], v89 offset:32768
	ds_read_b64 v[112:113], v88 offset:36864
	ds_read_b64 v[114:115], v89 offset:36864
	ds_read_b64 v[108:109], v88 offset:40960
	ds_read_b64 v[110:111], v89 offset:40960
	ds_read_b64 v[104:105], v88 offset:45056
	ds_read_b64 v[106:107], v89 offset:45056
	ds_read_b64 v[100:101], v88 offset:49152
	ds_read_b64 v[102:103], v89 offset:49152
	ds_read_b64 v[96:97], v88 offset:53248
	ds_read_b64 v[98:99], v89 offset:53248
	ds_read_b64 v[92:93], v88 offset:57344
	ds_read_b64 v[94:95], v89 offset:57344
	ds_read_b64 v[90:91], v89 offset:61440
	ds_read_b64 v[88:89], v88 offset:61440
	s_waitcnt lgkmcnt(0)
	v_mfma_f32_16x16x32_bf16 v[80:83], v[80:83], v[0:3], 0
	v_mfma_f32_16x16x32_bf16 v[124:127], v[120:123], v[4:7], v[80:83]
	v_mfma_f32_16x16x32_bf16 v[80:83], v[84:87], v[0:3], 0
	v_mfma_f32_16x16x32_bf16 v[120:123], v[128:131], v[4:7], v[80:83]
	v_mfma_f32_16x16x32_bf16 v[80:83], v[132:135], v[8:11], 0
	v_mfma_f32_16x16x32_bf16 v[84:87], v[140:143], v[12:15], v[80:83]
	v_mfma_f32_16x16x32_bf16 v[80:83], v[136:139], v[8:11], 0
	v_mfma_f32_16x16x32_bf16 v[80:83], v[216:219], v[12:15], v[80:83]
	s_nop 1
	v_max3_f32 v128, v124, v125, v126
	s_nop 0
	v_max3_f32 v128, v128, v127, v120
	v_max3_f32 v128, v128, v121, v122
	v_max_f32_e32 v128, v128, v123
	v_max3_f32 v129, v84, v85, v86
	v_max3_f32 v129, v129, v87, v80
	v_max3_f32 v129, v129, v81, v82
	v_max_f32_e32 v129, v129, v83
	v_pk_add_f32 v[172:173], v[170:171], s[8:9] op_sel_hi:[1,0]
	s_nop 0
	v_cmp_gt_f32_e32 vcc, v128, v172
	v_cmp_gt_f32_e64 s[0:1], v129, v173
	s_or_b64 vcc, vcc, s[0:1]
	s_cbranch_vccz .LBB0_706
	ds_bpermute_b32 v131, v188, v129
	ds_bpermute_b32 v130, v188, v128
	v_max_f32_e32 v129, v129, v129
	v_max_f32_e32 v128, v128, v128
	s_waitcnt lgkmcnt(1)
	v_max_f32_e32 v131, v131, v131
	s_waitcnt lgkmcnt(0)
	v_max_f32_e32 v130, v130, v130
	v_max_f32_e32 v129, v129, v131
	v_max_f32_e32 v128, v128, v130
	ds_bpermute_b32 v131, v187, v129
	ds_bpermute_b32 v130, v187, v128
	s_waitcnt lgkmcnt(1)
	v_max_f32_e32 v131, v131, v131
	s_waitcnt lgkmcnt(0)
	v_max_f32_e32 v130, v130, v130
	v_max_f32_e32 v129, v129, v131
	v_max_f32_e32 v128, v128, v130
	v_cmp_gt_f32_e32 vcc, v129, v173
	s_nop 1
	v_cndmask_b32_e32 v129, v171, v129, vcc
	v_cmp_gt_f32_e32 vcc, v128, v172
	s_nop 1
	v_cndmask_b32_e32 v128, v170, v128, vcc
	v_pk_add_f32 v[130:131], v[170:171], v[128:129] neg_lo:[0,1] neg_hi:[0,1]
	v_pk_add_f32 v[172:173], v[128:129], s[8:9] op_sel_hi:[1,0]
	v_exp_f32_e32 v130, v130
	v_exp_f32_e32 v132, v131
	v_mov_b64_e32 v[170:171], v[128:129]
	v_mov_b32_e32 v133, v130
	v_pk_mul_f32 v[66:67], v[66:67], v[130:131] op_sel_hi:[1,0]
	v_pk_mul_f32 v[64:65], v[64:65], v[130:131] op_sel_hi:[1,0]
	v_pk_mul_f32 v[58:59], v[58:59], v[130:131] op_sel_hi:[1,0]
	v_pk_mul_f32 v[56:57], v[56:57], v[130:131] op_sel_hi:[1,0]
	v_pk_mul_f32 v[50:51], v[50:51], v[130:131] op_sel_hi:[1,0]
	v_pk_mul_f32 v[48:49], v[48:49], v[130:131] op_sel_hi:[1,0]
	v_pk_mul_f32 v[42:43], v[42:43], v[130:131] op_sel_hi:[1,0]
	v_pk_mul_f32 v[40:41], v[40:41], v[130:131] op_sel_hi:[1,0]
	v_pk_mul_f32 v[34:35], v[34:35], v[130:131] op_sel_hi:[1,0]
	v_pk_mul_f32 v[32:33], v[32:33], v[130:131] op_sel_hi:[1,0]
	v_pk_mul_f32 v[26:27], v[26:27], v[130:131] op_sel_hi:[1,0]
	v_pk_mul_f32 v[24:25], v[24:25], v[130:131] op_sel_hi:[1,0]
	v_pk_mul_f32 v[18:19], v[18:19], v[130:131] op_sel_hi:[1,0]
	v_pk_mul_f32 v[16:17], v[16:17], v[130:131] op_sel_hi:[1,0]
	v_pk_mul_f32 v[74:75], v[74:75], v[130:131] op_sel_hi:[1,0]
	v_pk_mul_f32 v[72:73], v[72:73], v[130:131] op_sel_hi:[1,0]
	v_pk_mul_f32 v[174:175], v[174:175], v[132:133]
	v_pk_mul_f32 v[70:71], v[70:71], v[132:133] op_sel_hi:[1,0]
	v_pk_mul_f32 v[68:69], v[68:69], v[132:133] op_sel_hi:[1,0]
	v_pk_mul_f32 v[62:63], v[62:63], v[132:133] op_sel_hi:[1,0]
	v_pk_mul_f32 v[60:61], v[60:61], v[132:133] op_sel_hi:[1,0]
	v_pk_mul_f32 v[54:55], v[54:55], v[132:133] op_sel_hi:[1,0]
	v_pk_mul_f32 v[52:53], v[52:53], v[132:133] op_sel_hi:[1,0]
	v_pk_mul_f32 v[46:47], v[46:47], v[132:133] op_sel_hi:[1,0]
	v_pk_mul_f32 v[44:45], v[44:45], v[132:133] op_sel_hi:[1,0]
	v_pk_mul_f32 v[38:39], v[38:39], v[132:133] op_sel_hi:[1,0]
	v_pk_mul_f32 v[36:37], v[36:37], v[132:133] op_sel_hi:[1,0]
	v_pk_mul_f32 v[30:31], v[30:31], v[132:133] op_sel_hi:[1,0]
	v_pk_mul_f32 v[28:29], v[28:29], v[132:133] op_sel_hi:[1,0]
	v_pk_mul_f32 v[22:23], v[22:23], v[132:133] op_sel_hi:[1,0]
	v_pk_mul_f32 v[20:21], v[20:21], v[132:133] op_sel_hi:[1,0]
	v_pk_mul_f32 v[78:79], v[78:79], v[132:133] op_sel_hi:[1,0]
	v_pk_mul_f32 v[76:77], v[76:77], v[132:133] op_sel_hi:[1,0]
.LBB0_706:
	v_sub_f32_e32 v124, v124, v170
	v_sub_f32_e32 v84, v84, v171
	v_exp_f32_e32 v129, v124
	v_sub_f32_e32 v124, v125, v170
	v_exp_f32_e32 v128, v84
	v_sub_f32_e32 v84, v85, v171
	v_exp_f32_e32 v131, v124
	v_sub_f32_e32 v124, v126, v170
	v_exp_f32_e32 v130, v84
	v_sub_f32_e32 v84, v86, v171
	v_exp_f32_e32 v133, v124
	v_sub_f32_e32 v124, v127, v170
	v_exp_f32_e32 v132, v84
	v_sub_f32_e32 v84, v87, v171
	v_exp_f32_e32 v135, v124
	v_sub_f32_e32 v120, v120, v170
	v_exp_f32_e32 v134, v84
	v_sub_f32_e32 v80, v80, v171
	v_exp_f32_e32 v137, v120
	v_sub_f32_e32 v120, v121, v170
	v_exp_f32_e32 v136, v80
	v_pk_add_f32 v[84:85], v[128:129], 0 op_sel_hi:[1,0]
	v_sub_f32_e32 v80, v81, v171
	v_exp_f32_e32 v139, v120
	v_sub_f32_e32 v120, v122, v170
	v_pk_add_f32 v[84:85], v[130:131], v[84:85]
	v_exp_f32_e32 v138, v80
	v_sub_f32_e32 v80, v82, v171
	v_exp_f32_e32 v141, v120
	v_sub_f32_e32 v120, v123, v170
	v_pk_add_f32 v[84:85], v[132:133], v[84:85]
	v_exp_f32_e32 v140, v80
	v_sub_f32_e32 v80, v83, v171
	v_exp_f32_e32 v143, v120
	v_pk_add_f32 v[84:85], v[134:135], v[84:85]
	v_exp_f32_e32 v142, v80
	v_pk_add_f32 v[80:81], v[136:137], v[84:85]
	v_cvt_pk_bf16_f32 v124, v129, v131
	v_pk_add_f32 v[80:81], v[138:139], v[80:81]
	v_cvt_pk_bf16_f32 v125, v133, v135
	v_pk_add_f32 v[80:81], v[140:141], v[80:81]
	v_cvt_pk_bf16_f32 v126, v137, v139
	v_pk_add_f32 v[80:81], v[142:143], v[80:81]
	v_cvt_pk_bf16_f32 v127, v141, v143
	v_cvt_pk_bf16_f32 v120, v128, v130
	v_cvt_pk_bf16_f32 v121, v132, v134
	v_cvt_pk_bf16_f32 v122, v136, v138
	v_cvt_pk_bf16_f32 v123, v140, v142
	v_pk_add_f32 v[128:129], v[174:175], v[80:81]
	s_setprio 1
	s_waitcnt lgkmcnt(0)
	s_nop 1
	v_mfma_f32_16x16x32_bf16 v[80:83], v[116:119], v[124:127], v[64:67]
	v_mfma_f32_16x16x32_bf16 v[84:87], v[116:119], v[120:123], v[68:71]
	v_mfma_f32_16x16x32_bf16 v[68:71], v[112:115], v[120:123], v[60:63]
	v_mfma_f32_16x16x32_bf16 v[64:67], v[112:115], v[124:127], v[56:59]
	v_mfma_f32_16x16x32_bf16 v[56:59], v[108:111], v[124:127], v[48:51]
	v_mfma_f32_16x16x32_bf16 v[60:63], v[108:111], v[120:123], v[52:55]
	v_mfma_f32_16x16x32_bf16 v[52:55], v[104:107], v[120:123], v[44:47]
	v_mfma_f32_16x16x32_bf16 v[48:51], v[104:107], v[124:127], v[40:43]
	v_mfma_f32_16x16x32_bf16 v[40:43], v[100:103], v[124:127], v[32:35]
	v_mfma_f32_16x16x32_bf16 v[44:47], v[100:103], v[120:123], v[36:39]
	v_mfma_f32_16x16x32_bf16 v[36:39], v[96:99], v[120:123], v[28:31]
	v_mfma_f32_16x16x32_bf16 v[32:35], v[96:99], v[124:127], v[24:27]
	v_mfma_f32_16x16x32_bf16 v[24:27], v[92:95], v[124:127], v[16:19]
	v_mfma_f32_16x16x32_bf16 v[28:31], v[92:95], v[120:123], v[20:23]
	v_mfma_f32_16x16x32_bf16 v[16:19], v[88:91], v[124:127], v[72:75]
	v_mfma_f32_16x16x32_bf16 v[20:23], v[88:91], v[120:123], v[76:79]
	s_setprio 0
	s_nop 0
	ds_read_b128 v[72:75], v149 offset:8192
	ds_read_b128 v[76:79], v149 offset:12288
	ds_read_b128 v[120:123], v151 offset:8192
	ds_read_b128 v[130:133], v151 offset:12288
	ds_read_b128 v[134:137], v214 offset:8192
	ds_read_b128 v[138:141], v214 offset:12288
	ds_read_b128 v[174:177], v215 offset:8192
	ds_read_b128 v[216:219], v215 offset:12288
	v_add_u32_e32 v88, s17, v200
	v_add_u32_e32 v89, s17, v201
	ds_read_b64 v[116:117], v88 offset:32768
	ds_read_b64 v[118:119], v89 offset:32768
	ds_read_b64 v[112:113], v88 offset:36864
	ds_read_b64 v[114:115], v89 offset:36864
	ds_read_b64 v[108:109], v88 offset:40960
	ds_read_b64 v[110:111], v89 offset:40960
	ds_read_b64 v[104:105], v88 offset:45056
	ds_read_b64 v[106:107], v89 offset:45056
	ds_read_b64 v[100:101], v88 offset:49152
	ds_read_b64 v[102:103], v89 offset:49152
	ds_read_b64 v[96:97], v88 offset:53248
	ds_read_b64 v[98:99], v89 offset:53248
	ds_read_b64 v[92:93], v88 offset:57344
	ds_read_b64 v[94:95], v89 offset:57344
	ds_read_b64 v[90:91], v89 offset:61440
	ds_read_b64 v[88:89], v88 offset:61440
	s_waitcnt lgkmcnt(14)
	v_mfma_f32_16x16x32_bf16 v[72:75], v[72:75], v[0:3], 0
	s_waitcnt lgkmcnt(13)
	v_mfma_f32_16x16x32_bf16 v[124:127], v[120:123], v[4:7], v[72:75]
	v_mfma_f32_16x16x32_bf16 v[72:75], v[76:79], v[0:3], 0
	s_waitcnt lgkmcnt(12)
	v_mfma_f32_16x16x32_bf16 v[120:123], v[130:133], v[4:7], v[72:75]
	s_waitcnt lgkmcnt(11)
	v_mfma_f32_16x16x32_bf16 v[72:75], v[134:137], v[8:11], 0
	s_waitcnt lgkmcnt(9)
	v_mfma_f32_16x16x32_bf16 v[76:79], v[174:177], v[12:15], v[72:75]
	v_mfma_f32_16x16x32_bf16 v[72:75], v[138:141], v[8:11], 0
	s_waitcnt lgkmcnt(8)
	v_mfma_f32_16x16x32_bf16 v[72:75], v[216:219], v[12:15], v[72:75]
	v_max3_f32 v130, v124, v125, v126
	v_max3_f32 v130, v130, v127, v120
	v_max3_f32 v130, v130, v121, v122
	v_max_f32_e32 v130, v130, v123
	s_nop 0
	v_max3_f32 v131, v76, v77, v78
	s_nop 1
	v_max3_f32 v131, v131, v79, v72
	v_max3_f32 v131, v131, v73, v74
	v_max_f32_e32 v131, v131, v75
	v_cmp_gt_f32_e32 vcc, v130, v172
	v_cmp_gt_f32_e64 s[0:1], v131, v173
	s_or_b64 vcc, vcc, s[0:1]
	s_cbranch_vccz .LBB0_708
	ds_bpermute_b32 v132, v188, v130
	ds_bpermute_b32 v133, v188, v131
	v_max_f32_e32 v130, v130, v130
	v_max_f32_e32 v131, v131, v131
	s_waitcnt lgkmcnt(1)
	v_max_f32_e32 v132, v132, v132
	s_waitcnt lgkmcnt(0)
	v_max_f32_e32 v133, v133, v133
	v_max_f32_e32 v130, v130, v132
	v_max_f32_e32 v131, v131, v133
	ds_bpermute_b32 v132, v187, v130
	ds_bpermute_b32 v133, v187, v131
	s_waitcnt lgkmcnt(1)
	v_max_f32_e32 v132, v132, v132
	s_waitcnt lgkmcnt(0)
	v_max_f32_e32 v133, v133, v133
	v_max_f32_e32 v130, v130, v132
	v_max_f32_e32 v131, v131, v133
	v_add_f32_e32 v132, 0x41000000, v171
	v_cmp_gt_f32_e32 vcc, v131, v132
	s_nop 1
	v_cndmask_b32_e32 v175, v171, v131, vcc
	v_cmp_gt_f32_e32 vcc, v130, v172
	s_nop 1
	v_cndmask_b32_e32 v174, v170, v130, vcc
	v_pk_add_f32 v[130:131], v[170:171], v[174:175] neg_lo:[0,1] neg_hi:[0,1]
	v_pk_add_f32 v[172:173], v[174:175], s[8:9] op_sel_hi:[1,0]
	v_exp_f32_e32 v130, v130
	v_exp_f32_e32 v132, v131
	v_mov_b32_e32 v171, v175
	v_mov_b32_e32 v170, v174
	v_mov_b32_e32 v133, v130
	v_pk_mul_f32 v[82:83], v[82:83], v[130:131] op_sel_hi:[1,0]
	v_pk_mul_f32 v[80:81], v[80:81], v[130:131] op_sel_hi:[1,0]
	v_pk_mul_f32 v[66:67], v[66:67], v[130:131] op_sel_hi:[1,0]
	v_pk_mul_f32 v[64:65], v[64:65], v[130:131] op_sel_hi:[1,0]
	v_pk_mul_f32 v[58:59], v[58:59], v[130:131] op_sel_hi:[1,0]
	v_pk_mul_f32 v[56:57], v[56:57], v[130:131] op_sel_hi:[1,0]
	v_pk_mul_f32 v[50:51], v[50:51], v[130:131] op_sel_hi:[1,0]
	v_pk_mul_f32 v[48:49], v[48:49], v[130:131] op_sel_hi:[1,0]
	v_pk_mul_f32 v[42:43], v[42:43], v[130:131] op_sel_hi:[1,0]
	v_pk_mul_f32 v[40:41], v[40:41], v[130:131] op_sel_hi:[1,0]
	v_pk_mul_f32 v[34:35], v[34:35], v[130:131] op_sel_hi:[1,0]
	v_pk_mul_f32 v[32:33], v[32:33], v[130:131] op_sel_hi:[1,0]
	v_pk_mul_f32 v[26:27], v[26:27], v[130:131] op_sel_hi:[1,0]
	v_pk_mul_f32 v[24:25], v[24:25], v[130:131] op_sel_hi:[1,0]
	v_pk_mul_f32 v[18:19], v[18:19], v[130:131] op_sel_hi:[1,0]
	v_pk_mul_f32 v[16:17], v[16:17], v[130:131] op_sel_hi:[1,0]
	v_pk_mul_f32 v[128:129], v[128:129], v[132:133]
	v_pk_mul_f32 v[86:87], v[86:87], v[132:133] op_sel_hi:[1,0]
	v_pk_mul_f32 v[84:85], v[84:85], v[132:133] op_sel_hi:[1,0]
	v_pk_mul_f32 v[70:71], v[70:71], v[132:133] op_sel_hi:[1,0]
	v_pk_mul_f32 v[68:69], v[68:69], v[132:133] op_sel_hi:[1,0]
	v_pk_mul_f32 v[62:63], v[62:63], v[132:133] op_sel_hi:[1,0]
	v_pk_mul_f32 v[60:61], v[60:61], v[132:133] op_sel_hi:[1,0]
	v_pk_mul_f32 v[54:55], v[54:55], v[132:133] op_sel_hi:[1,0]
	v_pk_mul_f32 v[52:53], v[52:53], v[132:133] op_sel_hi:[1,0]
	v_pk_mul_f32 v[46:47], v[46:47], v[132:133] op_sel_hi:[1,0]
	v_pk_mul_f32 v[44:45], v[44:45], v[132:133] op_sel_hi:[1,0]
	v_pk_mul_f32 v[38:39], v[38:39], v[132:133] op_sel_hi:[1,0]
	v_pk_mul_f32 v[36:37], v[36:37], v[132:133] op_sel_hi:[1,0]
	v_pk_mul_f32 v[30:31], v[30:31], v[132:133] op_sel_hi:[1,0]
	v_pk_mul_f32 v[28:29], v[28:29], v[132:133] op_sel_hi:[1,0]
	v_pk_mul_f32 v[22:23], v[22:23], v[132:133] op_sel_hi:[1,0]
	v_pk_mul_f32 v[20:21], v[20:21], v[132:133] op_sel_hi:[1,0]
	s_branch .LBB0_709

.LBB0_709:
	v_sub_f32_e32 v124, v124, v170
	v_sub_f32_e32 v76, v76, v171
	v_exp_f32_e32 v131, v124
	v_sub_f32_e32 v124, v125, v170
	v_sub_f32_e32 v120, v120, v170
	v_exp_f32_e32 v130, v76
	v_sub_f32_e32 v76, v77, v171
	v_exp_f32_e32 v133, v124
	v_sub_f32_e32 v124, v126, v170
	v_exp_f32_e32 v137, v120
	v_sub_f32_e32 v120, v121, v170
	v_exp_f32_e32 v132, v76
	v_sub_f32_e32 v76, v78, v171
	v_exp_f32_e32 v135, v124
	v_sub_f32_e32 v124, v127, v170
	v_exp_f32_e32 v121, v120
	v_sub_f32_e32 v120, v122, v170
	v_exp_f32_e32 v134, v76
	v_sub_f32_e32 v76, v79, v171
	v_sub_f32_e32 v72, v72, v171
	v_exp_f32_e32 v127, v124
	v_exp_f32_e32 v139, v120
	v_sub_f32_e32 v120, v123, v170
	v_exp_f32_e32 v126, v76
	v_exp_f32_e32 v136, v72
	v_sub_f32_e32 v72, v73, v171
	v_exp_f32_e32 v141, v120
	v_pk_add_f32 v[76:77], v[130:131], 0 op_sel_hi:[1,0]
	v_exp_f32_e32 v120, v72
	v_sub_f32_e32 v72, v74, v171
	v_pk_add_f32 v[76:77], v[132:133], v[76:77]
	v_exp_f32_e32 v138, v72
	v_sub_f32_e32 v72, v75, v171
	v_exp_f32_e32 v140, v72
	v_pk_add_f32 v[72:73], v[134:135], v[76:77]
	v_cvt_pk_bf16_f32 v122, v131, v133
	v_pk_add_f32 v[72:73], v[126:127], v[72:73]
	v_cvt_pk_bf16_f32 v123, v135, v127
	v_pk_add_f32 v[72:73], v[136:137], v[72:73]
	v_cvt_pk_bf16_f32 v124, v137, v121
	v_pk_add_f32 v[72:73], v[120:121], v[72:73]
	v_cvt_pk_bf16_f32 v130, v130, v132
	v_pk_add_f32 v[72:73], v[138:139], v[72:73]
	v_cvt_pk_bf16_f32 v132, v136, v120
	v_pk_add_f32 v[72:73], v[140:141], v[72:73]
	v_cvt_pk_bf16_f32 v125, v139, v141
	v_pk_add_f32 v[120:121], v[128:129], v[72:73]
	v_cvt_pk_bf16_f32 v131, v134, v126
	v_cvt_pk_bf16_f32 v133, v138, v140
	s_setprio 1
	s_waitcnt lgkmcnt(0)
	s_nop 1
	v_mfma_f32_16x16x32_bf16 v[72:75], v[116:119], v[122:125], v[80:83]
	v_mfma_f32_16x16x32_bf16 v[56:59], v[108:111], v[122:125], v[56:59]
	v_mfma_f32_16x16x32_bf16 v[60:63], v[108:111], v[130:133], v[60:63]
	v_mfma_f32_16x16x32_bf16 v[40:43], v[100:103], v[122:125], v[40:43]
	v_mfma_f32_16x16x32_bf16 v[44:47], v[100:103], v[130:133], v[44:47]
	v_mfma_f32_16x16x32_bf16 v[76:79], v[116:119], v[130:133], v[84:87]
	v_mfma_f32_16x16x32_bf16 v[64:67], v[112:115], v[122:125], v[64:67]
	v_mfma_f32_16x16x32_bf16 v[68:71], v[112:115], v[130:133], v[68:71]
	v_mfma_f32_16x16x32_bf16 v[48:51], v[104:107], v[122:125], v[48:51]
	v_mfma_f32_16x16x32_bf16 v[52:55], v[104:107], v[130:133], v[52:55]
	v_mfma_f32_16x16x32_bf16 v[32:35], v[96:99], v[122:125], v[32:35]
	v_mfma_f32_16x16x32_bf16 v[36:39], v[96:99], v[130:133], v[36:39]
	v_mfma_f32_16x16x32_bf16 v[24:27], v[92:95], v[122:125], v[24:27]
	v_mfma_f32_16x16x32_bf16 v[28:31], v[92:95], v[130:133], v[28:31]
	v_mfma_f32_16x16x32_bf16 v[16:19], v[88:91], v[122:125], v[16:19]
	v_mfma_f32_16x16x32_bf16 v[20:23], v[88:91], v[130:133], v[20:23]
	s_setprio 0
	ds_read_b128 v[104:107], v149 offset:16384
	ds_read_b128 v[108:111], v149 offset:20480
	ds_read_b128 v[112:115], v151 offset:16384
	ds_read_b128 v[122:125], v151 offset:20480
	ds_read_b128 v[126:129], v214 offset:16384
	ds_read_b128 v[130:133], v214 offset:20480
	ds_read_b128 v[216:219], v215 offset:16384
	ds_read_b128 v[220:223], v215 offset:20480
	v_add_u32_e32 v116, s17, v202
	v_add_u32_e32 v117, s17, v203
	ds_read_b64 v[100:101], v116 offset:32768
	ds_read_b64 v[102:103], v117 offset:32768
	ds_read_b64 v[96:97], v116 offset:36864
	ds_read_b64 v[98:99], v117 offset:36864
	ds_read_b64 v[92:93], v116 offset:40960
	ds_read_b64 v[94:95], v117 offset:40960
	ds_read_b64 v[88:89], v116 offset:45056
	ds_read_b64 v[90:91], v117 offset:45056
	ds_read_b64 v[84:85], v116 offset:49152
	ds_read_b64 v[86:87], v117 offset:49152
	ds_read_b64 v[80:81], v116 offset:53248
	ds_read_b64 v[82:83], v117 offset:53248
	ds_read_b64 v[140:141], v116 offset:57344
	ds_read_b64 v[142:143], v117 offset:57344
	ds_read_b64 v[136:137], v116 offset:61440
	ds_read_b64 v[138:139], v117 offset:61440
	s_waitcnt lgkmcnt(14)
	v_mfma_f32_16x16x32_bf16 v[104:107], v[104:107], v[0:3], 0
	s_waitcnt lgkmcnt(13)
	v_mfma_f32_16x16x32_bf16 v[116:119], v[112:115], v[4:7], v[104:107]
	v_mfma_f32_16x16x32_bf16 v[104:107], v[108:111], v[0:3], 0
	s_waitcnt lgkmcnt(12)
	v_mfma_f32_16x16x32_bf16 v[112:115], v[122:125], v[4:7], v[104:107]
	s_waitcnt lgkmcnt(11)
	v_mfma_f32_16x16x32_bf16 v[104:107], v[126:129], v[8:11], 0
	s_waitcnt lgkmcnt(9)
	v_mfma_f32_16x16x32_bf16 v[108:111], v[216:219], v[12:15], v[104:107]
	v_mfma_f32_16x16x32_bf16 v[104:107], v[130:133], v[8:11], 0
	s_waitcnt lgkmcnt(8)
	v_mfma_f32_16x16x32_bf16 v[104:107], v[220:223], v[12:15], v[104:107]
	v_max3_f32 v122, v116, v117, v118
	v_max3_f32 v122, v122, v119, v112
	v_max3_f32 v122, v122, v113, v114
	v_max_f32_e32 v122, v122, v115
	s_nop 0
	v_max3_f32 v123, v108, v109, v110
	s_nop 1
	v_max3_f32 v123, v123, v111, v104
	v_max3_f32 v123, v123, v105, v106
	v_max_f32_e32 v123, v123, v107
	v_cmp_gt_f32_e32 vcc, v122, v172
	v_cmp_gt_f32_e64 s[0:1], v123, v173
	s_or_b64 vcc, vcc, s[0:1]
	s_cbranch_vccz .LBB0_711
	ds_bpermute_b32 v124, v188, v122
	ds_bpermute_b32 v125, v188, v123
	v_max_f32_e32 v122, v122, v122
	v_max_f32_e32 v123, v123, v123
	s_waitcnt lgkmcnt(1)
	v_max_f32_e32 v124, v124, v124
	s_waitcnt lgkmcnt(0)
	v_max_f32_e32 v125, v125, v125
	v_max_f32_e32 v122, v122, v124
	v_max_f32_e32 v123, v123, v125
	ds_bpermute_b32 v124, v187, v122
	ds_bpermute_b32 v125, v187, v123
	s_waitcnt lgkmcnt(1)
	v_max_f32_e32 v124, v124, v124
	s_waitcnt lgkmcnt(0)
	v_max_f32_e32 v125, v125, v125
	v_max_f32_e32 v122, v122, v124
	v_max_f32_e32 v123, v123, v125
	v_add_f32_e32 v124, 0x41000000, v171
	v_cmp_gt_f32_e32 vcc, v123, v124
	s_nop 1
	v_cndmask_b32_e32 v171, v175, v123, vcc
	v_cmp_gt_f32_e32 vcc, v122, v172
	s_nop 1
	v_cndmask_b32_e32 v170, v174, v122, vcc
	v_pk_add_f32 v[122:123], v[174:175], v[170:171] neg_lo:[0,1] neg_hi:[0,1]
	v_pk_add_f32 v[172:173], v[170:171], s[8:9] op_sel_hi:[1,0]
	v_exp_f32_e32 v122, v122
	v_exp_f32_e32 v124, v123
	v_mov_b64_e32 v[174:175], v[170:171]
	v_mov_b32_e32 v125, v122
	v_pk_mul_f32 v[74:75], v[74:75], v[122:123] op_sel_hi:[1,0]
	v_pk_mul_f32 v[72:73], v[72:73], v[122:123] op_sel_hi:[1,0]
	v_pk_mul_f32 v[66:67], v[66:67], v[122:123] op_sel_hi:[1,0]
	v_pk_mul_f32 v[64:65], v[64:65], v[122:123] op_sel_hi:[1,0]
	v_pk_mul_f32 v[58:59], v[58:59], v[122:123] op_sel_hi:[1,0]
	v_pk_mul_f32 v[56:57], v[56:57], v[122:123] op_sel_hi:[1,0]
	v_pk_mul_f32 v[50:51], v[50:51], v[122:123] op_sel_hi:[1,0]
	v_pk_mul_f32 v[48:49], v[48:49], v[122:123] op_sel_hi:[1,0]
	v_pk_mul_f32 v[42:43], v[42:43], v[122:123] op_sel_hi:[1,0]
	v_pk_mul_f32 v[40:41], v[40:41], v[122:123] op_sel_hi:[1,0]
	v_pk_mul_f32 v[34:35], v[34:35], v[122:123] op_sel_hi:[1,0]
	v_pk_mul_f32 v[32:33], v[32:33], v[122:123] op_sel_hi:[1,0]
	v_pk_mul_f32 v[26:27], v[26:27], v[122:123] op_sel_hi:[1,0]
	v_pk_mul_f32 v[24:25], v[24:25], v[122:123] op_sel_hi:[1,0]
	v_pk_mul_f32 v[18:19], v[18:19], v[122:123] op_sel_hi:[1,0]
	v_pk_mul_f32 v[16:17], v[16:17], v[122:123] op_sel_hi:[1,0]
	v_pk_mul_f32 v[120:121], v[120:121], v[124:125]
	v_pk_mul_f32 v[78:79], v[78:79], v[124:125] op_sel_hi:[1,0]
	v_pk_mul_f32 v[76:77], v[76:77], v[124:125] op_sel_hi:[1,0]
	v_pk_mul_f32 v[70:71], v[70:71], v[124:125] op_sel_hi:[1,0]
	v_pk_mul_f32 v[68:69], v[68:69], v[124:125] op_sel_hi:[1,0]
	v_pk_mul_f32 v[62:63], v[62:63], v[124:125] op_sel_hi:[1,0]
	v_pk_mul_f32 v[60:61], v[60:61], v[124:125] op_sel_hi:[1,0]
	v_pk_mul_f32 v[54:55], v[54:55], v[124:125] op_sel_hi:[1,0]
	v_pk_mul_f32 v[52:53], v[52:53], v[124:125] op_sel_hi:[1,0]
	v_pk_mul_f32 v[46:47], v[46:47], v[124:125] op_sel_hi:[1,0]
	v_pk_mul_f32 v[44:45], v[44:45], v[124:125] op_sel_hi:[1,0]
	v_pk_mul_f32 v[38:39], v[38:39], v[124:125] op_sel_hi:[1,0]
	v_pk_mul_f32 v[36:37], v[36:37], v[124:125] op_sel_hi:[1,0]
	v_pk_mul_f32 v[30:31], v[30:31], v[124:125] op_sel_hi:[1,0]
	v_pk_mul_f32 v[28:29], v[28:29], v[124:125] op_sel_hi:[1,0]
	v_pk_mul_f32 v[22:23], v[22:23], v[124:125] op_sel_hi:[1,0]
	v_pk_mul_f32 v[20:21], v[20:21], v[124:125] op_sel_hi:[1,0]
.LBB0_711:
	v_sub_f32_e32 v116, v116, v170
	v_exp_f32_e32 v123, v116
	v_sub_f32_e32 v116, v117, v170
	v_sub_f32_e32 v112, v112, v170
	v_exp_f32_e32 v117, v116
	v_sub_f32_e32 v116, v118, v170
	v_exp_f32_e32 v127, v112
	v_sub_f32_e32 v112, v113, v170
	v_sub_f32_e32 v108, v108, v171
	v_exp_f32_e32 v125, v116
	v_sub_f32_e32 v116, v119, v170
	v_exp_f32_e32 v113, v112
	v_sub_f32_e32 v112, v114, v170
	v_exp_f32_e32 v122, v108
	v_sub_f32_e32 v108, v109, v171
	v_sub_f32_e32 v104, v104, v171
	v_exp_f32_e32 v119, v116
	v_exp_f32_e32 v129, v112
	v_sub_f32_e32 v112, v115, v170
	v_exp_f32_e32 v116, v108
	v_sub_f32_e32 v108, v110, v171
	v_exp_f32_e32 v126, v104
	v_sub_f32_e32 v104, v105, v171
	v_exp_f32_e32 v115, v112
	v_exp_f32_e32 v124, v108
	v_sub_f32_e32 v108, v111, v171
	v_exp_f32_e32 v112, v104
	v_sub_f32_e32 v104, v106, v171
	v_exp_f32_e32 v118, v108
	v_exp_f32_e32 v128, v104
	v_sub_f32_e32 v104, v107, v171
	v_exp_f32_e32 v114, v104
	v_pk_add_f32 v[104:105], v[122:123], 0 op_sel_hi:[1,0]
	v_cvt_pk_bf16_f32 v216, v123, v117
	v_pk_add_f32 v[104:105], v[116:117], v[104:105]
	v_cvt_pk_bf16_f32 v217, v125, v119
	v_pk_add_f32 v[104:105], v[124:125], v[104:105]
	v_cvt_pk_bf16_f32 v218, v127, v113
	v_pk_add_f32 v[104:105], v[118:119], v[104:105]
	v_cvt_pk_bf16_f32 v219, v129, v115
	v_pk_add_f32 v[104:105], v[126:127], v[104:105]
	v_cvt_pk_bf16_f32 v220, v122, v116
	v_pk_add_f32 v[104:105], v[112:113], v[104:105]
	v_cvt_pk_bf16_f32 v221, v124, v118
	v_pk_add_f32 v[104:105], v[128:129], v[104:105]
	v_cvt_pk_bf16_f32 v222, v126, v112
	v_pk_add_f32 v[104:105], v[114:115], v[104:105]
	v_cvt_pk_bf16_f32 v223, v128, v114
	v_pk_add_f32 v[176:177], v[120:121], v[104:105]
	s_setprio 1
	s_waitcnt lgkmcnt(0)
	s_nop 1
	v_mfma_f32_16x16x32_bf16 v[124:127], v[96:99], v[216:219], v[64:67]
	v_mfma_f32_16x16x32_bf16 v[108:111], v[88:91], v[216:219], v[48:51]
	v_mfma_f32_16x16x32_bf16 v[132:135], v[100:103], v[216:219], v[72:75]
	v_mfma_f32_16x16x32_bf16 v[128:131], v[100:103], v[220:223], v[76:79]
	v_mfma_f32_16x16x32_bf16 v[120:123], v[96:99], v[220:223], v[68:71]
	v_mfma_f32_16x16x32_bf16 v[116:119], v[92:95], v[216:219], v[56:59]
	v_mfma_f32_16x16x32_bf16 v[112:115], v[92:95], v[220:223], v[60:63]
	v_mfma_f32_16x16x32_bf16 v[92:95], v[80:83], v[216:219], v[32:35]
	v_mfma_f32_16x16x32_bf16 v[104:107], v[88:91], v[220:223], v[52:55]
	v_mfma_f32_16x16x32_bf16 v[100:103], v[84:87], v[216:219], v[40:43]
	v_mfma_f32_16x16x32_bf16 v[96:99], v[84:87], v[220:223], v[44:47]
	v_mfma_f32_16x16x32_bf16 v[88:91], v[80:83], v[220:223], v[36:39]
	v_mfma_f32_16x16x32_bf16 v[84:87], v[140:143], v[216:219], v[24:27]
	v_mfma_f32_16x16x32_bf16 v[80:83], v[140:143], v[220:223], v[28:31]
	v_mfma_f32_16x16x32_bf16 v[72:75], v[136:139], v[216:219], v[16:19]
	v_mfma_f32_16x16x32_bf16 v[76:79], v[136:139], v[220:223], v[20:23]
	s_setprio 0
	ds_read_b128 v[40:43], v149 offset:24576
	ds_read_b128 v[44:47], v149 offset:28672
	ds_read_b128 v[48:51], v151 offset:24576
	ds_read_b128 v[56:59], v151 offset:28672
	ds_read_b128 v[60:63], v214 offset:24576
	ds_read_b128 v[64:67], v214 offset:28672
	ds_read_b128 v[68:71], v215 offset:24576
	ds_read_b128 v[214:217], v215 offset:28672
	v_add_u32_e32 v52, s17, v204
	v_add_u32_e32 v53, s17, v205
	ds_read_b64 v[36:37], v52 offset:32768
	ds_read_b64 v[38:39], v53 offset:32768
	ds_read_b64 v[32:33], v52 offset:36864
	ds_read_b64 v[34:35], v53 offset:36864
	ds_read_b64 v[28:29], v52 offset:40960
	ds_read_b64 v[30:31], v53 offset:40960
	ds_read_b64 v[24:25], v52 offset:45056
	ds_read_b64 v[26:27], v53 offset:45056
	ds_read_b64 v[20:21], v52 offset:49152
	ds_read_b64 v[22:23], v53 offset:49152
	ds_read_b64 v[16:17], v52 offset:53248
	ds_read_b64 v[18:19], v53 offset:53248
	ds_read_b64 v[140:141], v52 offset:57344
	ds_read_b64 v[142:143], v53 offset:57344
	ds_read_b64 v[136:137], v52 offset:61440
	ds_read_b64 v[138:139], v53 offset:61440
	s_waitcnt lgkmcnt(14)
	v_mfma_f32_16x16x32_bf16 v[40:43], v[40:43], v[0:3], 0
	s_waitcnt lgkmcnt(13)
	v_mfma_f32_16x16x32_bf16 v[52:55], v[48:51], v[4:7], v[40:43]
	v_mfma_f32_16x16x32_bf16 v[40:43], v[44:47], v[0:3], 0
	s_waitcnt lgkmcnt(12)
	v_mfma_f32_16x16x32_bf16 v[48:51], v[56:59], v[4:7], v[40:43]
	s_waitcnt lgkmcnt(11)
	v_mfma_f32_16x16x32_bf16 v[40:43], v[60:63], v[8:11], 0
	s_waitcnt lgkmcnt(9)
	v_mfma_f32_16x16x32_bf16 v[44:47], v[68:71], v[12:15], v[40:43]
	v_mfma_f32_16x16x32_bf16 v[40:43], v[64:67], v[8:11], 0
	s_waitcnt lgkmcnt(8)
	v_mfma_f32_16x16x32_bf16 v[40:43], v[214:217], v[12:15], v[40:43]
	v_max3_f32 v56, v52, v53, v54
	v_max3_f32 v56, v56, v55, v48
	v_max3_f32 v56, v56, v49, v50
	v_max_f32_e32 v56, v56, v51
	s_nop 0
	v_max3_f32 v57, v44, v45, v46
	s_nop 1
	v_max3_f32 v57, v57, v47, v40
	v_max3_f32 v57, v57, v41, v42
	v_max_f32_e32 v57, v57, v43
	v_cmp_gt_f32_e32 vcc, v56, v172
	v_cmp_gt_f32_e64 s[0:1], v57, v173
	s_or_b64 vcc, vcc, s[0:1]
	s_cbranch_vccnz .LBB0_700
	v_mov_b32_e32 v57, v171
	v_mov_b32_e32 v56, v170
	v_mov_b64_e32 v[170:171], v[174:175]
	s_branch .LBB0_701

.LBB0_2243:
	s_and_b32 s0, s14, 0x10000
	s_add_i32 s17, s0, 0
	v_add_u32_e32 v88, s17, v191
	v_add_u32_e32 v149, v88, v194
	v_add_u32_e32 v151, v88, v195
	v_add_u32_e32 v213, v88, v196
	v_add_u32_e32 v214, v88, v197
	v_add_u32_e32 v88, s17, v192
	v_add_u32_e32 v89, s17, v198
	ds_read_b128 v[80:83], v149
	ds_read_b128 v[84:87], v149 offset:4096
	ds_read_b128 v[120:123], v151
	ds_read_b128 v[128:131], v151 offset:4096
	ds_read_b128 v[132:135], v213
	ds_read_b128 v[136:139], v213 offset:4096
	ds_read_b128 v[140:143], v214
	ds_read_b128 v[216:219], v214 offset:4096
	s_waitcnt vmcnt(0)
	ds_read_b64 v[116:117], v88 offset:32768
	ds_read_b64 v[118:119], v89 offset:32768
	ds_read_b64 v[112:113], v88 offset:36864
	ds_read_b64 v[114:115], v89 offset:36864
	ds_read_b64 v[108:109], v88 offset:40960
	ds_read_b64 v[110:111], v89 offset:40960
	ds_read_b64 v[104:105], v88 offset:45056
	ds_read_b64 v[106:107], v89 offset:45056
	ds_read_b64 v[100:101], v88 offset:49152
	ds_read_b64 v[102:103], v89 offset:49152
	ds_read_b64 v[96:97], v88 offset:53248
	ds_read_b64 v[98:99], v89 offset:53248
	ds_read_b64 v[92:93], v88 offset:57344
	ds_read_b64 v[94:95], v89 offset:57344
	ds_read_b64 v[90:91], v89 offset:61440
	ds_read_b64 v[88:89], v88 offset:61440
	s_waitcnt lgkmcnt(0)
	v_mfma_f32_16x16x32_bf16 v[80:83], v[80:83], v[0:3], 0
	v_mfma_f32_16x16x32_bf16 v[124:127], v[120:123], v[4:7], v[80:83]
	v_mfma_f32_16x16x32_bf16 v[80:83], v[84:87], v[0:3], 0
	v_mfma_f32_16x16x32_bf16 v[120:123], v[128:131], v[4:7], v[80:83]
	v_mfma_f32_16x16x32_bf16 v[80:83], v[132:135], v[8:11], 0
	v_mfma_f32_16x16x32_bf16 v[84:87], v[140:143], v[12:15], v[80:83]
	v_mfma_f32_16x16x32_bf16 v[80:83], v[136:139], v[8:11], 0
	v_mfma_f32_16x16x32_bf16 v[80:83], v[216:219], v[12:15], v[80:83]
	s_nop 1
	v_max3_f32 v128, v124, v125, v126
	s_nop 0
	v_max3_f32 v128, v128, v127, v120
	v_max3_f32 v128, v128, v121, v122
	v_max_f32_e32 v128, v128, v123
	v_max3_f32 v129, v84, v85, v86
	v_max3_f32 v129, v129, v87, v80
	v_max3_f32 v129, v129, v81, v82
	v_max_f32_e32 v129, v129, v83
	v_pk_add_f32 v[172:173], v[170:171], s[8:9] op_sel_hi:[1,0]
	s_nop 0
	v_cmp_gt_f32_e32 vcc, v128, v172
	v_cmp_gt_f32_e64 s[0:1], v129, v173
	s_or_b64 vcc, vcc, s[0:1]
	s_cbranch_vccz .LBB0_2245
	ds_bpermute_b32 v131, v187, v129
	ds_bpermute_b32 v130, v187, v128
	v_max_f32_e32 v129, v129, v129
	v_max_f32_e32 v128, v128, v128
	s_waitcnt lgkmcnt(1)
	v_max_f32_e32 v131, v131, v131
	s_waitcnt lgkmcnt(0)
	v_max_f32_e32 v130, v130, v130
	v_max_f32_e32 v129, v129, v131
	v_max_f32_e32 v128, v128, v130
	ds_bpermute_b32 v131, v186, v129
	ds_bpermute_b32 v130, v186, v128
	s_waitcnt lgkmcnt(1)
	v_max_f32_e32 v131, v131, v131
	s_waitcnt lgkmcnt(0)
	v_max_f32_e32 v130, v130, v130
	v_max_f32_e32 v129, v129, v131
	v_max_f32_e32 v128, v128, v130
	v_cmp_gt_f32_e32 vcc, v129, v173
	s_nop 1
	v_cndmask_b32_e32 v129, v171, v129, vcc
	v_cmp_gt_f32_e32 vcc, v128, v172
	s_nop 1
	v_cndmask_b32_e32 v128, v170, v128, vcc
	v_pk_add_f32 v[130:131], v[170:171], v[128:129] neg_lo:[0,1] neg_hi:[0,1]
	v_pk_add_f32 v[172:173], v[128:129], s[8:9] op_sel_hi:[1,0]
	v_exp_f32_e32 v130, v130
	v_exp_f32_e32 v132, v131
	v_mov_b64_e32 v[170:171], v[128:129]
	v_mov_b32_e32 v133, v130
	v_pk_mul_f32 v[66:67], v[66:67], v[130:131] op_sel_hi:[1,0]
	v_pk_mul_f32 v[64:65], v[64:65], v[130:131] op_sel_hi:[1,0]
	v_pk_mul_f32 v[58:59], v[58:59], v[130:131] op_sel_hi:[1,0]
	v_pk_mul_f32 v[56:57], v[56:57], v[130:131] op_sel_hi:[1,0]
	v_pk_mul_f32 v[50:51], v[50:51], v[130:131] op_sel_hi:[1,0]
	v_pk_mul_f32 v[48:49], v[48:49], v[130:131] op_sel_hi:[1,0]
	v_pk_mul_f32 v[42:43], v[42:43], v[130:131] op_sel_hi:[1,0]
	v_pk_mul_f32 v[40:41], v[40:41], v[130:131] op_sel_hi:[1,0]
	v_pk_mul_f32 v[34:35], v[34:35], v[130:131] op_sel_hi:[1,0]
	v_pk_mul_f32 v[32:33], v[32:33], v[130:131] op_sel_hi:[1,0]
	v_pk_mul_f32 v[26:27], v[26:27], v[130:131] op_sel_hi:[1,0]
	v_pk_mul_f32 v[24:25], v[24:25], v[130:131] op_sel_hi:[1,0]
	v_pk_mul_f32 v[18:19], v[18:19], v[130:131] op_sel_hi:[1,0]
	v_pk_mul_f32 v[16:17], v[16:17], v[130:131] op_sel_hi:[1,0]
	v_pk_mul_f32 v[74:75], v[74:75], v[130:131] op_sel_hi:[1,0]
	v_pk_mul_f32 v[72:73], v[72:73], v[130:131] op_sel_hi:[1,0]
	v_pk_mul_f32 v[174:175], v[174:175], v[132:133]
	v_pk_mul_f32 v[70:71], v[70:71], v[132:133] op_sel_hi:[1,0]
	v_pk_mul_f32 v[68:69], v[68:69], v[132:133] op_sel_hi:[1,0]
	v_pk_mul_f32 v[62:63], v[62:63], v[132:133] op_sel_hi:[1,0]
	v_pk_mul_f32 v[60:61], v[60:61], v[132:133] op_sel_hi:[1,0]
	v_pk_mul_f32 v[54:55], v[54:55], v[132:133] op_sel_hi:[1,0]
	v_pk_mul_f32 v[52:53], v[52:53], v[132:133] op_sel_hi:[1,0]
	v_pk_mul_f32 v[46:47], v[46:47], v[132:133] op_sel_hi:[1,0]
	v_pk_mul_f32 v[44:45], v[44:45], v[132:133] op_sel_hi:[1,0]
	v_pk_mul_f32 v[38:39], v[38:39], v[132:133] op_sel_hi:[1,0]
	v_pk_mul_f32 v[36:37], v[36:37], v[132:133] op_sel_hi:[1,0]
	v_pk_mul_f32 v[30:31], v[30:31], v[132:133] op_sel_hi:[1,0]
	v_pk_mul_f32 v[28:29], v[28:29], v[132:133] op_sel_hi:[1,0]
	v_pk_mul_f32 v[22:23], v[22:23], v[132:133] op_sel_hi:[1,0]
	v_pk_mul_f32 v[20:21], v[20:21], v[132:133] op_sel_hi:[1,0]
	v_pk_mul_f32 v[78:79], v[78:79], v[132:133] op_sel_hi:[1,0]
	v_pk_mul_f32 v[76:77], v[76:77], v[132:133] op_sel_hi:[1,0]
.LBB0_2245:
	v_sub_f32_e32 v124, v124, v170
	v_sub_f32_e32 v84, v84, v171
	v_exp_f32_e32 v129, v124
	v_sub_f32_e32 v124, v125, v170
	v_exp_f32_e32 v128, v84
	v_sub_f32_e32 v84, v85, v171
	v_exp_f32_e32 v131, v124
	v_sub_f32_e32 v124, v126, v170
	v_exp_f32_e32 v130, v84
	v_sub_f32_e32 v84, v86, v171
	v_exp_f32_e32 v133, v124
	v_sub_f32_e32 v124, v127, v170
	v_exp_f32_e32 v132, v84
	v_sub_f32_e32 v84, v87, v171
	v_exp_f32_e32 v135, v124
	v_sub_f32_e32 v120, v120, v170
	v_exp_f32_e32 v134, v84
	v_sub_f32_e32 v80, v80, v171
	v_exp_f32_e32 v137, v120
	v_sub_f32_e32 v120, v121, v170
	v_exp_f32_e32 v136, v80
	v_pk_add_f32 v[84:85], v[128:129], 0 op_sel_hi:[1,0]
	v_sub_f32_e32 v80, v81, v171
	v_exp_f32_e32 v139, v120
	v_sub_f32_e32 v120, v122, v170
	v_pk_add_f32 v[84:85], v[130:131], v[84:85]
	v_exp_f32_e32 v138, v80
	v_sub_f32_e32 v80, v82, v171
	v_exp_f32_e32 v141, v120
	v_sub_f32_e32 v120, v123, v170
	v_pk_add_f32 v[84:85], v[132:133], v[84:85]
	v_exp_f32_e32 v140, v80
	v_sub_f32_e32 v80, v83, v171
	v_exp_f32_e32 v143, v120
	v_pk_add_f32 v[84:85], v[134:135], v[84:85]
	v_exp_f32_e32 v142, v80
	v_pk_add_f32 v[80:81], v[136:137], v[84:85]
	v_cvt_pk_bf16_f32 v124, v129, v131
	v_pk_add_f32 v[80:81], v[138:139], v[80:81]
	v_cvt_pk_bf16_f32 v125, v133, v135
	v_pk_add_f32 v[80:81], v[140:141], v[80:81]
	v_cvt_pk_bf16_f32 v126, v137, v139
	v_pk_add_f32 v[80:81], v[142:143], v[80:81]
	v_cvt_pk_bf16_f32 v127, v141, v143
	v_cvt_pk_bf16_f32 v120, v128, v130
	v_cvt_pk_bf16_f32 v121, v132, v134
	v_cvt_pk_bf16_f32 v122, v136, v138
	v_cvt_pk_bf16_f32 v123, v140, v142
	v_pk_add_f32 v[128:129], v[174:175], v[80:81]
	s_setprio 1
	s_waitcnt lgkmcnt(0)
	s_nop 1
	v_mfma_f32_16x16x32_bf16 v[80:83], v[116:119], v[124:127], v[64:67]
	v_mfma_f32_16x16x32_bf16 v[84:87], v[116:119], v[120:123], v[68:71]
	v_mfma_f32_16x16x32_bf16 v[68:71], v[112:115], v[120:123], v[60:63]
	v_mfma_f32_16x16x32_bf16 v[64:67], v[112:115], v[124:127], v[56:59]
	v_mfma_f32_16x16x32_bf16 v[56:59], v[108:111], v[124:127], v[48:51]
	v_mfma_f32_16x16x32_bf16 v[60:63], v[108:111], v[120:123], v[52:55]
	v_mfma_f32_16x16x32_bf16 v[52:55], v[104:107], v[120:123], v[44:47]
	v_mfma_f32_16x16x32_bf16 v[48:51], v[104:107], v[124:127], v[40:43]
	v_mfma_f32_16x16x32_bf16 v[40:43], v[100:103], v[124:127], v[32:35]
	v_mfma_f32_16x16x32_bf16 v[44:47], v[100:103], v[120:123], v[36:39]
	v_mfma_f32_16x16x32_bf16 v[36:39], v[96:99], v[120:123], v[28:31]
	v_mfma_f32_16x16x32_bf16 v[32:35], v[96:99], v[124:127], v[24:27]
	v_mfma_f32_16x16x32_bf16 v[24:27], v[92:95], v[124:127], v[16:19]
	v_mfma_f32_16x16x32_bf16 v[28:31], v[92:95], v[120:123], v[20:23]
	v_mfma_f32_16x16x32_bf16 v[16:19], v[88:91], v[124:127], v[72:75]
	v_mfma_f32_16x16x32_bf16 v[20:23], v[88:91], v[120:123], v[76:79]
	s_setprio 0
	s_nop 0
	ds_read_b128 v[72:75], v149 offset:8192
	ds_read_b128 v[76:79], v149 offset:12288
	ds_read_b128 v[120:123], v151 offset:8192
	ds_read_b128 v[130:133], v151 offset:12288
	ds_read_b128 v[134:137], v213 offset:8192
	ds_read_b128 v[138:141], v213 offset:12288
	ds_read_b128 v[174:177], v214 offset:8192
	ds_read_b128 v[216:219], v214 offset:12288
	v_add_u32_e32 v88, s17, v199
	v_add_u32_e32 v89, s17, v200
	ds_read_b64 v[116:117], v88 offset:32768
	ds_read_b64 v[118:119], v89 offset:32768
	ds_read_b64 v[112:113], v88 offset:36864
	ds_read_b64 v[114:115], v89 offset:36864
	ds_read_b64 v[108:109], v88 offset:40960
	ds_read_b64 v[110:111], v89 offset:40960
	ds_read_b64 v[104:105], v88 offset:45056
	ds_read_b64 v[106:107], v89 offset:45056
	ds_read_b64 v[100:101], v88 offset:49152
	ds_read_b64 v[102:103], v89 offset:49152
	ds_read_b64 v[96:97], v88 offset:53248
	ds_read_b64 v[98:99], v89 offset:53248
	ds_read_b64 v[92:93], v88 offset:57344
	ds_read_b64 v[94:95], v89 offset:57344
	ds_read_b64 v[90:91], v89 offset:61440
	ds_read_b64 v[88:89], v88 offset:61440
	s_waitcnt lgkmcnt(14)
	v_mfma_f32_16x16x32_bf16 v[72:75], v[72:75], v[0:3], 0
	s_waitcnt lgkmcnt(13)
	v_mfma_f32_16x16x32_bf16 v[124:127], v[120:123], v[4:7], v[72:75]
	v_mfma_f32_16x16x32_bf16 v[72:75], v[76:79], v[0:3], 0
	s_waitcnt lgkmcnt(12)
	v_mfma_f32_16x16x32_bf16 v[120:123], v[130:133], v[4:7], v[72:75]
	s_waitcnt lgkmcnt(11)
	v_mfma_f32_16x16x32_bf16 v[72:75], v[134:137], v[8:11], 0
	s_waitcnt lgkmcnt(9)
	v_mfma_f32_16x16x32_bf16 v[76:79], v[174:177], v[12:15], v[72:75]
	v_mfma_f32_16x16x32_bf16 v[72:75], v[138:141], v[8:11], 0
	s_waitcnt lgkmcnt(8)
	v_mfma_f32_16x16x32_bf16 v[72:75], v[216:219], v[12:15], v[72:75]
	v_max3_f32 v130, v124, v125, v126
	v_max3_f32 v130, v130, v127, v120
	v_max3_f32 v130, v130, v121, v122
	v_max_f32_e32 v130, v130, v123
	s_nop 0
	v_max3_f32 v131, v76, v77, v78
	s_nop 1
	v_max3_f32 v131, v131, v79, v72
	v_max3_f32 v131, v131, v73, v74
	v_max_f32_e32 v131, v131, v75
	v_cmp_gt_f32_e32 vcc, v130, v172
	v_cmp_gt_f32_e64 s[0:1], v131, v173
	s_or_b64 vcc, vcc, s[0:1]
	s_cbranch_vccz .LBB0_2247
	ds_bpermute_b32 v132, v187, v130
	ds_bpermute_b32 v133, v187, v131
	v_max_f32_e32 v130, v130, v130
	v_max_f32_e32 v131, v131, v131
	s_waitcnt lgkmcnt(1)
	v_max_f32_e32 v132, v132, v132
	s_waitcnt lgkmcnt(0)
	v_max_f32_e32 v133, v133, v133
	v_max_f32_e32 v130, v130, v132
	v_max_f32_e32 v131, v131, v133
	ds_bpermute_b32 v132, v186, v130
	ds_bpermute_b32 v133, v186, v131
	s_waitcnt lgkmcnt(1)
	v_max_f32_e32 v132, v132, v132
	s_waitcnt lgkmcnt(0)
	v_max_f32_e32 v133, v133, v133
	v_max_f32_e32 v130, v130, v132
	v_max_f32_e32 v131, v131, v133
	v_add_f32_e32 v132, 0x41000000, v171
	v_cmp_gt_f32_e32 vcc, v131, v132
	s_nop 1
	v_cndmask_b32_e32 v175, v171, v131, vcc
	v_cmp_gt_f32_e32 vcc, v130, v172
	s_nop 1
	v_cndmask_b32_e32 v174, v170, v130, vcc
	v_pk_add_f32 v[130:131], v[170:171], v[174:175] neg_lo:[0,1] neg_hi:[0,1]
	v_pk_add_f32 v[172:173], v[174:175], s[8:9] op_sel_hi:[1,0]
	v_exp_f32_e32 v130, v130
	v_exp_f32_e32 v132, v131
	v_mov_b32_e32 v171, v175
	v_mov_b32_e32 v170, v174
	v_mov_b32_e32 v133, v130
	v_pk_mul_f32 v[82:83], v[82:83], v[130:131] op_sel_hi:[1,0]
	v_pk_mul_f32 v[80:81], v[80:81], v[130:131] op_sel_hi:[1,0]
	v_pk_mul_f32 v[66:67], v[66:67], v[130:131] op_sel_hi:[1,0]
	v_pk_mul_f32 v[64:65], v[64:65], v[130:131] op_sel_hi:[1,0]
	v_pk_mul_f32 v[58:59], v[58:59], v[130:131] op_sel_hi:[1,0]
	v_pk_mul_f32 v[56:57], v[56:57], v[130:131] op_sel_hi:[1,0]
	v_pk_mul_f32 v[50:51], v[50:51], v[130:131] op_sel_hi:[1,0]
	v_pk_mul_f32 v[48:49], v[48:49], v[130:131] op_sel_hi:[1,0]
	v_pk_mul_f32 v[42:43], v[42:43], v[130:131] op_sel_hi:[1,0]
	v_pk_mul_f32 v[40:41], v[40:41], v[130:131] op_sel_hi:[1,0]
	v_pk_mul_f32 v[34:35], v[34:35], v[130:131] op_sel_hi:[1,0]
	v_pk_mul_f32 v[32:33], v[32:33], v[130:131] op_sel_hi:[1,0]
	v_pk_mul_f32 v[26:27], v[26:27], v[130:131] op_sel_hi:[1,0]
	v_pk_mul_f32 v[24:25], v[24:25], v[130:131] op_sel_hi:[1,0]
	v_pk_mul_f32 v[18:19], v[18:19], v[130:131] op_sel_hi:[1,0]
	v_pk_mul_f32 v[16:17], v[16:17], v[130:131] op_sel_hi:[1,0]
	v_pk_mul_f32 v[128:129], v[128:129], v[132:133]
	v_pk_mul_f32 v[86:87], v[86:87], v[132:133] op_sel_hi:[1,0]
	v_pk_mul_f32 v[84:85], v[84:85], v[132:133] op_sel_hi:[1,0]
	v_pk_mul_f32 v[70:71], v[70:71], v[132:133] op_sel_hi:[1,0]
	v_pk_mul_f32 v[68:69], v[68:69], v[132:133] op_sel_hi:[1,0]
	v_pk_mul_f32 v[62:63], v[62:63], v[132:133] op_sel_hi:[1,0]
	v_pk_mul_f32 v[60:61], v[60:61], v[132:133] op_sel_hi:[1,0]
	v_pk_mul_f32 v[54:55], v[54:55], v[132:133] op_sel_hi:[1,0]
	v_pk_mul_f32 v[52:53], v[52:53], v[132:133] op_sel_hi:[1,0]
	v_pk_mul_f32 v[46:47], v[46:47], v[132:133] op_sel_hi:[1,0]
	v_pk_mul_f32 v[44:45], v[44:45], v[132:133] op_sel_hi:[1,0]
	v_pk_mul_f32 v[38:39], v[38:39], v[132:133] op_sel_hi:[1,0]
	v_pk_mul_f32 v[36:37], v[36:37], v[132:133] op_sel_hi:[1,0]
	v_pk_mul_f32 v[30:31], v[30:31], v[132:133] op_sel_hi:[1,0]
	v_pk_mul_f32 v[28:29], v[28:29], v[132:133] op_sel_hi:[1,0]
	v_pk_mul_f32 v[22:23], v[22:23], v[132:133] op_sel_hi:[1,0]
	v_pk_mul_f32 v[20:21], v[20:21], v[132:133] op_sel_hi:[1,0]
	s_branch .LBB0_2248

.LBB0_2248:
	v_sub_f32_e32 v124, v124, v170
	v_sub_f32_e32 v76, v76, v171
	v_exp_f32_e32 v131, v124
	v_sub_f32_e32 v124, v125, v170
	v_sub_f32_e32 v120, v120, v170
	v_exp_f32_e32 v130, v76
	v_sub_f32_e32 v76, v77, v171
	v_exp_f32_e32 v133, v124
	v_sub_f32_e32 v124, v126, v170
	v_exp_f32_e32 v137, v120
	v_sub_f32_e32 v120, v121, v170
	v_exp_f32_e32 v132, v76
	v_sub_f32_e32 v76, v78, v171
	v_exp_f32_e32 v135, v124
	v_sub_f32_e32 v124, v127, v170
	v_exp_f32_e32 v121, v120
	v_sub_f32_e32 v120, v122, v170
	v_exp_f32_e32 v134, v76
	v_sub_f32_e32 v76, v79, v171
	v_sub_f32_e32 v72, v72, v171
	v_exp_f32_e32 v127, v124
	v_exp_f32_e32 v139, v120
	v_sub_f32_e32 v120, v123, v170
	v_exp_f32_e32 v126, v76
	v_exp_f32_e32 v136, v72
	v_sub_f32_e32 v72, v73, v171
	v_exp_f32_e32 v141, v120
	v_pk_add_f32 v[76:77], v[130:131], 0 op_sel_hi:[1,0]
	v_exp_f32_e32 v120, v72
	v_sub_f32_e32 v72, v74, v171
	v_pk_add_f32 v[76:77], v[132:133], v[76:77]
	v_exp_f32_e32 v138, v72
	v_sub_f32_e32 v72, v75, v171
	v_exp_f32_e32 v140, v72
	v_pk_add_f32 v[72:73], v[134:135], v[76:77]
	v_cvt_pk_bf16_f32 v122, v131, v133
	v_pk_add_f32 v[72:73], v[126:127], v[72:73]
	v_cvt_pk_bf16_f32 v123, v135, v127
	v_pk_add_f32 v[72:73], v[136:137], v[72:73]
	v_cvt_pk_bf16_f32 v124, v137, v121
	v_pk_add_f32 v[72:73], v[120:121], v[72:73]
	v_cvt_pk_bf16_f32 v130, v130, v132
	v_pk_add_f32 v[72:73], v[138:139], v[72:73]
	v_cvt_pk_bf16_f32 v132, v136, v120
	v_pk_add_f32 v[72:73], v[140:141], v[72:73]
	v_cvt_pk_bf16_f32 v125, v139, v141
	v_pk_add_f32 v[120:121], v[128:129], v[72:73]
	v_cvt_pk_bf16_f32 v131, v134, v126
	v_cvt_pk_bf16_f32 v133, v138, v140
	s_setprio 1
	s_waitcnt lgkmcnt(0)
	s_nop 1
	v_mfma_f32_16x16x32_bf16 v[72:75], v[116:119], v[122:125], v[80:83]
	v_mfma_f32_16x16x32_bf16 v[56:59], v[108:111], v[122:125], v[56:59]
	v_mfma_f32_16x16x32_bf16 v[60:63], v[108:111], v[130:133], v[60:63]
	v_mfma_f32_16x16x32_bf16 v[40:43], v[100:103], v[122:125], v[40:43]
	v_mfma_f32_16x16x32_bf16 v[44:47], v[100:103], v[130:133], v[44:47]
	v_mfma_f32_16x16x32_bf16 v[76:79], v[116:119], v[130:133], v[84:87]
	v_mfma_f32_16x16x32_bf16 v[64:67], v[112:115], v[122:125], v[64:67]
	v_mfma_f32_16x16x32_bf16 v[68:71], v[112:115], v[130:133], v[68:71]
	v_mfma_f32_16x16x32_bf16 v[48:51], v[104:107], v[122:125], v[48:51]
	v_mfma_f32_16x16x32_bf16 v[52:55], v[104:107], v[130:133], v[52:55]
	v_mfma_f32_16x16x32_bf16 v[32:35], v[96:99], v[122:125], v[32:35]
	v_mfma_f32_16x16x32_bf16 v[36:39], v[96:99], v[130:133], v[36:39]
	v_mfma_f32_16x16x32_bf16 v[24:27], v[92:95], v[122:125], v[24:27]
	v_mfma_f32_16x16x32_bf16 v[28:31], v[92:95], v[130:133], v[28:31]
	v_mfma_f32_16x16x32_bf16 v[16:19], v[88:91], v[122:125], v[16:19]
	v_mfma_f32_16x16x32_bf16 v[20:23], v[88:91], v[130:133], v[20:23]
	s_setprio 0
	ds_read_b128 v[104:107], v149 offset:16384
	ds_read_b128 v[108:111], v149 offset:20480
	ds_read_b128 v[112:115], v151 offset:16384
	ds_read_b128 v[122:125], v151 offset:20480
	ds_read_b128 v[126:129], v213 offset:16384
	ds_read_b128 v[130:133], v213 offset:20480
	ds_read_b128 v[216:219], v214 offset:16384
	ds_read_b128 v[220:223], v214 offset:20480
	v_add_u32_e32 v116, s17, v201
	v_add_u32_e32 v117, s17, v202
	ds_read_b64 v[100:101], v116 offset:32768
	ds_read_b64 v[102:103], v117 offset:32768
	ds_read_b64 v[96:97], v116 offset:36864
	ds_read_b64 v[98:99], v117 offset:36864
	ds_read_b64 v[92:93], v116 offset:40960
	ds_read_b64 v[94:95], v117 offset:40960
	ds_read_b64 v[88:89], v116 offset:45056
	ds_read_b64 v[90:91], v117 offset:45056
	ds_read_b64 v[84:85], v116 offset:49152
	ds_read_b64 v[86:87], v117 offset:49152
	ds_read_b64 v[80:81], v116 offset:53248
	ds_read_b64 v[82:83], v117 offset:53248
	ds_read_b64 v[140:141], v116 offset:57344
	ds_read_b64 v[142:143], v117 offset:57344
	ds_read_b64 v[136:137], v116 offset:61440
	ds_read_b64 v[138:139], v117 offset:61440
	s_waitcnt lgkmcnt(14)
	v_mfma_f32_16x16x32_bf16 v[104:107], v[104:107], v[0:3], 0
	s_waitcnt lgkmcnt(13)
	v_mfma_f32_16x16x32_bf16 v[116:119], v[112:115], v[4:7], v[104:107]
	v_mfma_f32_16x16x32_bf16 v[104:107], v[108:111], v[0:3], 0
	s_waitcnt lgkmcnt(12)
	v_mfma_f32_16x16x32_bf16 v[112:115], v[122:125], v[4:7], v[104:107]
	s_waitcnt lgkmcnt(11)
	v_mfma_f32_16x16x32_bf16 v[104:107], v[126:129], v[8:11], 0
	s_waitcnt lgkmcnt(9)
	v_mfma_f32_16x16x32_bf16 v[108:111], v[216:219], v[12:15], v[104:107]
	v_mfma_f32_16x16x32_bf16 v[104:107], v[130:133], v[8:11], 0
	s_waitcnt lgkmcnt(8)
	v_mfma_f32_16x16x32_bf16 v[104:107], v[220:223], v[12:15], v[104:107]
	v_max3_f32 v122, v116, v117, v118
	v_max3_f32 v122, v122, v119, v112
	v_max3_f32 v122, v122, v113, v114
	v_max_f32_e32 v122, v122, v115
	s_nop 0
	v_max3_f32 v123, v108, v109, v110
	s_nop 1
	v_max3_f32 v123, v123, v111, v104
	v_max3_f32 v123, v123, v105, v106
	v_max_f32_e32 v123, v123, v107
	v_cmp_gt_f32_e32 vcc, v122, v172
	v_cmp_gt_f32_e64 s[0:1], v123, v173
	s_or_b64 vcc, vcc, s[0:1]
	s_cbranch_vccz .LBB0_2250
	ds_bpermute_b32 v124, v187, v122
	ds_bpermute_b32 v125, v187, v123
	v_max_f32_e32 v122, v122, v122
	v_max_f32_e32 v123, v123, v123
	s_waitcnt lgkmcnt(1)
	v_max_f32_e32 v124, v124, v124
	s_waitcnt lgkmcnt(0)
	v_max_f32_e32 v125, v125, v125
	v_max_f32_e32 v122, v122, v124
	v_max_f32_e32 v123, v123, v125
	ds_bpermute_b32 v124, v186, v122
	ds_bpermute_b32 v125, v186, v123
	s_waitcnt lgkmcnt(1)
	v_max_f32_e32 v124, v124, v124
	s_waitcnt lgkmcnt(0)
	v_max_f32_e32 v125, v125, v125
	v_max_f32_e32 v122, v122, v124
	v_max_f32_e32 v123, v123, v125
	v_add_f32_e32 v124, 0x41000000, v171
	v_cmp_gt_f32_e32 vcc, v123, v124
	s_nop 1
	v_cndmask_b32_e32 v171, v175, v123, vcc
	v_cmp_gt_f32_e32 vcc, v122, v172
	s_nop 1
	v_cndmask_b32_e32 v170, v174, v122, vcc
	v_pk_add_f32 v[122:123], v[174:175], v[170:171] neg_lo:[0,1] neg_hi:[0,1]
	v_pk_add_f32 v[172:173], v[170:171], s[8:9] op_sel_hi:[1,0]
	v_exp_f32_e32 v122, v122
	v_exp_f32_e32 v124, v123
	v_mov_b64_e32 v[174:175], v[170:171]
	v_mov_b32_e32 v125, v122
	v_pk_mul_f32 v[74:75], v[74:75], v[122:123] op_sel_hi:[1,0]
	v_pk_mul_f32 v[72:73], v[72:73], v[122:123] op_sel_hi:[1,0]
	v_pk_mul_f32 v[66:67], v[66:67], v[122:123] op_sel_hi:[1,0]
	v_pk_mul_f32 v[64:65], v[64:65], v[122:123] op_sel_hi:[1,0]
	v_pk_mul_f32 v[58:59], v[58:59], v[122:123] op_sel_hi:[1,0]
	v_pk_mul_f32 v[56:57], v[56:57], v[122:123] op_sel_hi:[1,0]
	v_pk_mul_f32 v[50:51], v[50:51], v[122:123] op_sel_hi:[1,0]
	v_pk_mul_f32 v[48:49], v[48:49], v[122:123] op_sel_hi:[1,0]
	v_pk_mul_f32 v[42:43], v[42:43], v[122:123] op_sel_hi:[1,0]
	v_pk_mul_f32 v[40:41], v[40:41], v[122:123] op_sel_hi:[1,0]
	v_pk_mul_f32 v[34:35], v[34:35], v[122:123] op_sel_hi:[1,0]
	v_pk_mul_f32 v[32:33], v[32:33], v[122:123] op_sel_hi:[1,0]
	v_pk_mul_f32 v[26:27], v[26:27], v[122:123] op_sel_hi:[1,0]
	v_pk_mul_f32 v[24:25], v[24:25], v[122:123] op_sel_hi:[1,0]
	v_pk_mul_f32 v[18:19], v[18:19], v[122:123] op_sel_hi:[1,0]
	v_pk_mul_f32 v[16:17], v[16:17], v[122:123] op_sel_hi:[1,0]
	v_pk_mul_f32 v[120:121], v[120:121], v[124:125]
	v_pk_mul_f32 v[78:79], v[78:79], v[124:125] op_sel_hi:[1,0]
	v_pk_mul_f32 v[76:77], v[76:77], v[124:125] op_sel_hi:[1,0]
	v_pk_mul_f32 v[70:71], v[70:71], v[124:125] op_sel_hi:[1,0]
	v_pk_mul_f32 v[68:69], v[68:69], v[124:125] op_sel_hi:[1,0]
	v_pk_mul_f32 v[62:63], v[62:63], v[124:125] op_sel_hi:[1,0]
	v_pk_mul_f32 v[60:61], v[60:61], v[124:125] op_sel_hi:[1,0]
	v_pk_mul_f32 v[54:55], v[54:55], v[124:125] op_sel_hi:[1,0]
	v_pk_mul_f32 v[52:53], v[52:53], v[124:125] op_sel_hi:[1,0]
	v_pk_mul_f32 v[46:47], v[46:47], v[124:125] op_sel_hi:[1,0]
	v_pk_mul_f32 v[44:45], v[44:45], v[124:125] op_sel_hi:[1,0]
	v_pk_mul_f32 v[38:39], v[38:39], v[124:125] op_sel_hi:[1,0]
	v_pk_mul_f32 v[36:37], v[36:37], v[124:125] op_sel_hi:[1,0]
	v_pk_mul_f32 v[30:31], v[30:31], v[124:125] op_sel_hi:[1,0]
	v_pk_mul_f32 v[28:29], v[28:29], v[124:125] op_sel_hi:[1,0]
	v_pk_mul_f32 v[22:23], v[22:23], v[124:125] op_sel_hi:[1,0]
	v_pk_mul_f32 v[20:21], v[20:21], v[124:125] op_sel_hi:[1,0]
.LBB0_2250:
	v_sub_f32_e32 v116, v116, v170
	v_exp_f32_e32 v123, v116
	v_sub_f32_e32 v116, v117, v170
	v_sub_f32_e32 v112, v112, v170
	v_exp_f32_e32 v117, v116
	v_sub_f32_e32 v116, v118, v170
	v_exp_f32_e32 v127, v112
	v_sub_f32_e32 v112, v113, v170
	v_sub_f32_e32 v108, v108, v171
	v_exp_f32_e32 v125, v116
	v_sub_f32_e32 v116, v119, v170
	v_exp_f32_e32 v113, v112
	v_sub_f32_e32 v112, v114, v170
	v_exp_f32_e32 v122, v108
	v_sub_f32_e32 v108, v109, v171
	v_sub_f32_e32 v104, v104, v171
	v_exp_f32_e32 v119, v116
	v_exp_f32_e32 v129, v112
	v_sub_f32_e32 v112, v115, v170
	v_exp_f32_e32 v116, v108
	v_sub_f32_e32 v108, v110, v171
	v_exp_f32_e32 v126, v104
	v_sub_f32_e32 v104, v105, v171
	v_exp_f32_e32 v115, v112
	v_exp_f32_e32 v124, v108
	v_sub_f32_e32 v108, v111, v171
	v_exp_f32_e32 v112, v104
	v_sub_f32_e32 v104, v106, v171
	v_exp_f32_e32 v118, v108
	v_exp_f32_e32 v128, v104
	v_sub_f32_e32 v104, v107, v171
	v_exp_f32_e32 v114, v104
	v_pk_add_f32 v[104:105], v[122:123], 0 op_sel_hi:[1,0]
	v_cvt_pk_bf16_f32 v216, v123, v117
	v_pk_add_f32 v[104:105], v[116:117], v[104:105]
	v_cvt_pk_bf16_f32 v217, v125, v119
	v_pk_add_f32 v[104:105], v[124:125], v[104:105]
	v_cvt_pk_bf16_f32 v218, v127, v113
	v_pk_add_f32 v[104:105], v[118:119], v[104:105]
	v_cvt_pk_bf16_f32 v219, v129, v115
	v_pk_add_f32 v[104:105], v[126:127], v[104:105]
	v_cvt_pk_bf16_f32 v220, v122, v116
	v_pk_add_f32 v[104:105], v[112:113], v[104:105]
	v_cvt_pk_bf16_f32 v221, v124, v118
	v_pk_add_f32 v[104:105], v[128:129], v[104:105]
	v_cvt_pk_bf16_f32 v222, v126, v112
	v_pk_add_f32 v[104:105], v[114:115], v[104:105]
	v_cvt_pk_bf16_f32 v223, v128, v114
	v_pk_add_f32 v[176:177], v[120:121], v[104:105]
	s_setprio 1
	s_waitcnt lgkmcnt(0)
	s_nop 1
	v_mfma_f32_16x16x32_bf16 v[124:127], v[96:99], v[216:219], v[64:67]
	v_mfma_f32_16x16x32_bf16 v[108:111], v[88:91], v[216:219], v[48:51]
	v_mfma_f32_16x16x32_bf16 v[132:135], v[100:103], v[216:219], v[72:75]
	v_mfma_f32_16x16x32_bf16 v[128:131], v[100:103], v[220:223], v[76:79]
	v_mfma_f32_16x16x32_bf16 v[120:123], v[96:99], v[220:223], v[68:71]
	v_mfma_f32_16x16x32_bf16 v[116:119], v[92:95], v[216:219], v[56:59]
	v_mfma_f32_16x16x32_bf16 v[112:115], v[92:95], v[220:223], v[60:63]
	v_mfma_f32_16x16x32_bf16 v[92:95], v[80:83], v[216:219], v[32:35]
	v_mfma_f32_16x16x32_bf16 v[104:107], v[88:91], v[220:223], v[52:55]
	v_mfma_f32_16x16x32_bf16 v[100:103], v[84:87], v[216:219], v[40:43]
	v_mfma_f32_16x16x32_bf16 v[96:99], v[84:87], v[220:223], v[44:47]
	v_mfma_f32_16x16x32_bf16 v[88:91], v[80:83], v[220:223], v[36:39]
	v_mfma_f32_16x16x32_bf16 v[84:87], v[140:143], v[216:219], v[24:27]
	v_mfma_f32_16x16x32_bf16 v[80:83], v[140:143], v[220:223], v[28:31]
	v_mfma_f32_16x16x32_bf16 v[72:75], v[136:139], v[216:219], v[16:19]
	v_mfma_f32_16x16x32_bf16 v[76:79], v[136:139], v[220:223], v[20:23]
	s_setprio 0
	ds_read_b128 v[40:43], v149 offset:24576
	ds_read_b128 v[44:47], v149 offset:28672
	ds_read_b128 v[48:51], v151 offset:24576
	ds_read_b128 v[56:59], v151 offset:28672
	ds_read_b128 v[60:63], v213 offset:24576
	ds_read_b128 v[64:67], v213 offset:28672
	ds_read_b128 v[68:71], v214 offset:24576
	ds_read_b128 v[214:217], v214 offset:28672
	v_add_u32_e32 v52, s17, v203
	v_add_u32_e32 v53, s17, v204
	ds_read_b64 v[36:37], v52 offset:32768
	ds_read_b64 v[38:39], v53 offset:32768
	ds_read_b64 v[32:33], v52 offset:36864
	ds_read_b64 v[34:35], v53 offset:36864
	ds_read_b64 v[28:29], v52 offset:40960
	ds_read_b64 v[30:31], v53 offset:40960
	ds_read_b64 v[24:25], v52 offset:45056
	ds_read_b64 v[26:27], v53 offset:45056
	ds_read_b64 v[20:21], v52 offset:49152
	ds_read_b64 v[22:23], v53 offset:49152
	ds_read_b64 v[16:17], v52 offset:53248
	ds_read_b64 v[18:19], v53 offset:53248
	ds_read_b64 v[140:141], v52 offset:57344
	ds_read_b64 v[142:143], v53 offset:57344
	ds_read_b64 v[136:137], v52 offset:61440
	ds_read_b64 v[138:139], v53 offset:61440
	s_waitcnt lgkmcnt(14)
	v_mfma_f32_16x16x32_bf16 v[40:43], v[40:43], v[0:3], 0
	s_waitcnt lgkmcnt(13)
	v_mfma_f32_16x16x32_bf16 v[52:55], v[48:51], v[4:7], v[40:43]
	v_mfma_f32_16x16x32_bf16 v[40:43], v[44:47], v[0:3], 0
	s_waitcnt lgkmcnt(12)
	v_mfma_f32_16x16x32_bf16 v[48:51], v[56:59], v[4:7], v[40:43]
	s_waitcnt lgkmcnt(11)
	v_mfma_f32_16x16x32_bf16 v[40:43], v[60:63], v[8:11], 0
	s_waitcnt lgkmcnt(9)
	v_mfma_f32_16x16x32_bf16 v[44:47], v[68:71], v[12:15], v[40:43]
	v_mfma_f32_16x16x32_bf16 v[40:43], v[64:67], v[8:11], 0
	s_waitcnt lgkmcnt(8)
	v_mfma_f32_16x16x32_bf16 v[40:43], v[214:217], v[12:15], v[40:43]
	v_max3_f32 v56, v52, v53, v54
	v_max3_f32 v56, v56, v55, v48
	v_max3_f32 v56, v56, v49, v50
	v_max_f32_e32 v56, v56, v51
	s_nop 0
	v_max3_f32 v57, v44, v45, v46
	s_nop 1
	v_max3_f32 v57, v57, v47, v40
	v_max3_f32 v57, v57, v41, v42
	v_max_f32_e32 v57, v57, v43
	v_cmp_gt_f32_e32 vcc, v56, v172
	v_cmp_gt_f32_e64 s[0:1], v57, v173
	s_or_b64 vcc, vcc, s[0:1]
	s_cbranch_vccnz .LBB0_2239
	v_mov_b32_e32 v57, v171
	v_mov_b32_e32 v56, v170
	v_mov_b64_e32 v[170:171], v[174:175]
	s_branch .LBB0_2240
